# same as v29 but K tile ds_write moved behind the last counted lgkmcnt so no counted wait depends on LDS write/read retirement order
# baseline (speedup 1.0000x reference)
; #define SBAR() __builtin_amdgcn_sched_barrier(0)
; #define KWRITE(b, src0, src1) do { if constexpr (ND0 == 4) { *(bf16x8*)(K_lds + (b) * SHM_K + KSWZ(kr, kcb)) = src0; } \
;     else { int kc = sc * 2; *(bf16x8*)(K_lds + (b) * SHM_K + KSWZ(sr, kc)) = src0; *(bf16x8*)(K_lds + (b) * SHM_K + KSWZ(32 + sr, kc)) = src1; } } while (0)
; template <int OFF> __device__ __forceinline__ s16x4 tr_read(int vb) {
;   s16x4 r; asm volatile("ds_read_b64_tr_b16 %0, %1 offset:%2" : "=&v"(r) : "v"(vb), "i"(OFF) : "memory"); return r;
; }
; template <int D0> __device__ __forceinline__ void pv_one(f32x16& od, int vb, bf16x8 pa0, bf16x8 pa1, bf16x8 pa2, bf16x8 pa3) {
;   const s16x4 l0 = tr_read<v_rd_off(D0, 0, 0)>(vb), h0 = tr_read<v_rd_off(D0, 0, 1)>(vb), l1 = tr_read<v_rd_off(D0, 1, 0)>(vb), h1 = tr_read<v_rd_off(D0, 1, 1)>(vb);
;   const s16x4 l2 = tr_read<v_rd_off(D0, 2, 0)>(vb), h2 = tr_read<v_rd_off(D0, 2, 1)>(vb), l3 = tr_read<v_rd_off(D0, 3, 0)>(vb), h3 = tr_read<v_rd_off(D0, 3, 1)>(vb);
;   asm volatile("s_waitcnt lgkmcnt(0)" ::: "memory"); SBAR();
;     ...
;   od = __builtin_amdgcn_mfma_f32_32x32x16_bf16(pa0, PK(l0, h0), od, 0, 0, 0);
;   od = __builtin_amdgcn_mfma_f32_32x32x16_bf16(pa1, PK(l1, h1), od, 0, 0, 0);
;   od = __builtin_amdgcn_mfma_f32_32x32x16_bf16(pa2, PK(l2, h2), od, 0, 0, 0);
;   od = __builtin_amdgcn_mfma_f32_32x32x16_bf16(pa3, PK(l3, h3), od, 0, 0, 0);
;     ...
; }
; __device__ __forceinline__ void pv_d0(f32x16* o, int vb, bf16x8 pa0, bf16x8 pa1, bf16x8 pa2, bf16x8 pa3) {
;   pv_one<0>(o[0], vb, pa0, pa1, pa2, pa3); pv_one<1>(o[1], vb, pa0, pa1, pa2, pa3); pv_one<2>(o[2], vb, pa0, pa1, pa2, pa3); pv_one<3>(o[3], vb, pa0, pa1, pa2, pa3);
; }
; template <int ND0, int LDQ, int LDK, int LDO> ...
;     ...
;   for (int j = 1; j + 1 < NT; j += 2) {
;     SBAR(); qkt<ND0>(pB0, pB1, Kq1, qr, r32, hi);
;     finishSM(pA0, pA1, alA, l_reg, pa0, pa1, pa2, pa3); SBAR();
;     SLOAD_B((j + 2) * KVBLK); SBAR();
;     pv_d0(o, vb0, pa0, pa1, pa2, pa3); KWRITE(0, ks0a, ks1a); PSM(pB0, pB1, mnB, alB);
;     __syncthreads(); SWAIT(); VWRITE_A(0);
;     RESC(alB); __syncthreads();
;     SBAR(); qkt<ND0>(pA0, pA1, Kq0, qr, r32, hi);
;     finishSM(pB0, pB1, alB, l_reg, pa0, pa1, pa2, pa3); SBAR();
;     if (j + 3 < NT) SLOAD_A((j + 3) * KVBLK); SBAR();
;     pv_d0(o, vb0 + (int)SHM_V, pa0, pa1, pa2, pa3); KWRITE(1, ks0b, ks1b); PSM(pA0, pA1, mnA, alA);
.LBB0_147:
	v_max_f32_e32 v180, v97, v97
	v_max_f32_e32 v182, v96, v96
	v_max_f32_e32 v180, v182, v180
	v_max3_f32 v180, v180, v98, v99
	v_max3_f32 v180, v180, v100, v101
	v_max3_f32 v180, v180, v102, v103
	v_max3_f32 v180, v180, v104, v105
	v_max3_f32 v180, v180, v106, v107
	v_max3_f32 v180, v180, v108, v109
	v_max3_f32 v180, v180, v110, v111
	v_max3_f32 v180, v180, v80, v81
	v_max3_f32 v180, v180, v82, v83
	v_max3_f32 v180, v180, v84, v85
	v_max3_f32 v180, v180, v86, v87
	v_max3_f32 v180, v180, v88, v89
	v_max3_f32 v180, v180, v90, v91
	v_max3_f32 v180, v180, v92, v93
	v_max3_f32 v180, v180, v94, v95
	v_mov_b32_e32 v182, v180
	s_nop 1
	v_permlane32_swap_b32_e32 v180, v182
	v_max_f32_e32 v182, v182, v182
	v_max_f32_e32 v180, v180, v180
	v_max_f32_e32 v180, v180, v182
	s_waitcnt lgkmcnt(4)
	v_mfma_f32_32x32x16_bf16 v[0:15], v[64:67], v[210:213], v[0:15]
	ds_read_b64_tr_b16 v[210:211], v194 offset:0x200
	ds_read_b64_tr_b16 v[212:213], v194 offset:0xa00
	v_mfma_f32_32x32x16_bf16 v[0:15], v[68:71], v[214:217], v[0:15]
	ds_read_b64_tr_b16 v[214:215], v194 offset:0x1200
	ds_read_b64_tr_b16 v[216:217], v194 offset:0x1a00
	s_waitcnt lgkmcnt(4)
	v_mfma_f32_32x32x16_bf16 v[0:15], v[72:75], v[218:221], v[0:15]
	ds_read_b64_tr_b16 v[218:219], v194 offset:0x2200
	ds_read_b64_tr_b16 v[220:221], v194 offset:0x2a00
	v_mfma_f32_32x32x16_bf16 v[0:15], v[76:79], v[222:225], v[0:15]
	ds_read_b64_tr_b16 v[222:223], v194 offset:0x3200
	ds_read_b64_tr_b16 v[224:225], v194 offset:0x3a00
	s_waitcnt lgkmcnt(4)
	v_mfma_f32_32x32x16_bf16 v[48:63], v[64:67], v[210:213], v[48:63]
	ds_read_b64_tr_b16 v[210:211], v194 offset:0x400
	ds_read_b64_tr_b16 v[212:213], v194 offset:0xc00
	v_mfma_f32_32x32x16_bf16 v[48:63], v[68:71], v[214:217], v[48:63]
	ds_read_b64_tr_b16 v[214:215], v194 offset:0x1400
	ds_read_b64_tr_b16 v[216:217], v194 offset:0x1c00
	s_waitcnt lgkmcnt(4)
	v_mfma_f32_32x32x16_bf16 v[48:63], v[72:75], v[218:221], v[48:63]
	ds_read_b64_tr_b16 v[218:219], v194 offset:0x2400
	ds_read_b64_tr_b16 v[220:221], v194 offset:0x2c00
	v_mfma_f32_32x32x16_bf16 v[48:63], v[76:79], v[222:225], v[48:63]
	ds_read_b64_tr_b16 v[222:223], v194 offset:0x3400
	ds_read_b64_tr_b16 v[224:225], v194 offset:0x3c00
	s_waitcnt lgkmcnt(4)
	v_mfma_f32_32x32x16_bf16 v[32:47], v[64:67], v[210:213], v[32:47]
	ds_read_b64_tr_b16 v[210:211], v194 offset:0x600
	ds_read_b64_tr_b16 v[212:213], v194 offset:0xe00
	v_mfma_f32_32x32x16_bf16 v[32:47], v[68:71], v[214:217], v[32:47]
	ds_read_b64_tr_b16 v[214:215], v194 offset:0x1600
	ds_read_b64_tr_b16 v[216:217], v194 offset:0x1e00
	s_waitcnt lgkmcnt(4)
	v_mfma_f32_32x32x16_bf16 v[32:47], v[72:75], v[218:221], v[32:47]
	ds_read_b64_tr_b16 v[218:219], v194 offset:0x2600
	ds_read_b64_tr_b16 v[220:221], v194 offset:0x2e00
	v_mfma_f32_32x32x16_bf16 v[32:47], v[76:79], v[222:225], v[32:47]
	ds_read_b64_tr_b16 v[222:223], v194 offset:0x3600
	ds_read_b64_tr_b16 v[224:225], v194 offset:0x3e00
	s_waitcnt lgkmcnt(4)
	v_mfma_f32_32x32x16_bf16 v[16:31], v[64:67], v[210:213], v[16:31]
	v_mfma_f32_32x32x16_bf16 v[16:31], v[68:71], v[214:217], v[16:31]
	s_waitcnt lgkmcnt(0)
	v_mfma_f32_32x32x16_bf16 v[16:31], v[72:75], v[218:221], v[16:31]
	s_waitcnt vmcnt(4)
	ds_write_b128 v195, v[150:153] offset:32768
	ds_write_b128 v196, v[146:149] offset:32768
	v_mfma_f32_32x32x16_bf16 v[16:31], v[76:79], v[222:225], v[16:31]
	v_cmp_ge_f32_e32 vcc, s45, v180
	s_cmp_eq_u64 vcc, exec
	v_mov_b32_e32 v210, 1.0
	s_cbranch_scc0 .LBB0_164

; #define SBAR() __builtin_amdgcn_sched_barrier(0)
; #define KWRITE(b, src0, src1) do { if constexpr (ND0 == 4) { *(bf16x8*)(K_lds + (b) * SHM_K + KSWZ(kr, kcb)) = src0; } \
;     else { int kc = sc * 2; *(bf16x8*)(K_lds + (b) * SHM_K + KSWZ(sr, kc)) = src0; *(bf16x8*)(K_lds + (b) * SHM_K + KSWZ(32 + sr, kc)) = src1; } } while (0)
; template <int OFF> __device__ __forceinline__ s16x4 tr_read(int vb) {
;   s16x4 r; asm volatile("ds_read_b64_tr_b16 %0, %1 offset:%2" : "=&v"(r) : "v"(vb), "i"(OFF) : "memory"); return r;
; }
; template <int D0> __device__ __forceinline__ void pv_one(f32x16& od, int vb, bf16x8 pa0, bf16x8 pa1, bf16x8 pa2, bf16x8 pa3) {
;   const s16x4 l0 = tr_read<v_rd_off(D0, 0, 0)>(vb), h0 = tr_read<v_rd_off(D0, 0, 1)>(vb), l1 = tr_read<v_rd_off(D0, 1, 0)>(vb), h1 = tr_read<v_rd_off(D0, 1, 1)>(vb);
;   const s16x4 l2 = tr_read<v_rd_off(D0, 2, 0)>(vb), h2 = tr_read<v_rd_off(D0, 2, 1)>(vb), l3 = tr_read<v_rd_off(D0, 3, 0)>(vb), h3 = tr_read<v_rd_off(D0, 3, 1)>(vb);
;   asm volatile("s_waitcnt lgkmcnt(0)" ::: "memory"); SBAR();
;     ...
;   od = __builtin_amdgcn_mfma_f32_32x32x16_bf16(pa0, PK(l0, h0), od, 0, 0, 0);
;   od = __builtin_amdgcn_mfma_f32_32x32x16_bf16(pa1, PK(l1, h1), od, 0, 0, 0);
;   od = __builtin_amdgcn_mfma_f32_32x32x16_bf16(pa2, PK(l2, h2), od, 0, 0, 0);
;   od = __builtin_amdgcn_mfma_f32_32x32x16_bf16(pa3, PK(l3, h3), od, 0, 0, 0);
;     ...
; }
; __device__ __forceinline__ void pv_d0(f32x16* o, int vb, bf16x8 pa0, bf16x8 pa1, bf16x8 pa2, bf16x8 pa3) {
;   pv_one<0>(o[0], vb, pa0, pa1, pa2, pa3); pv_one<1>(o[1], vb, pa0, pa1, pa2, pa3); pv_one<2>(o[2], vb, pa0, pa1, pa2, pa3); pv_one<3>(o[3], vb, pa0, pa1, pa2, pa3);
; }
; template <int ND0, int LDQ, int LDK, int LDO> ...
;     ...
;   for (int j = 1; j + 1 < NT; j += 2) {
;     SBAR(); qkt<ND0>(pB0, pB1, Kq1, qr, r32, hi);
;     finishSM(pA0, pA1, alA, l_reg, pa0, pa1, pa2, pa3); SBAR();
;     SLOAD_B((j + 2) * KVBLK); SBAR();
;     pv_d0(o, vb0, pa0, pa1, pa2, pa3); KWRITE(0, ks0a, ks1a); PSM(pB0, pB1, mnB, alB);
;     __syncthreads(); SWAIT(); VWRITE_A(0);
;     RESC(alB); __syncthreads();
;     SBAR(); qkt<ND0>(pA0, pA1, Kq0, qr, r32, hi);
;     finishSM(pB0, pB1, alB, l_reg, pa0, pa1, pa2, pa3); SBAR();
;     if (j + 3 < NT) SLOAD_A((j + 3) * KVBLK); SBAR();
;     pv_d0(o, vb0 + (int)SHM_V, pa0, pa1, pa2, pa3); KWRITE(1, ks0b, ks1b); PSM(pA0, pA1, mnA, alA);
.LBB0_156:
	v_max_f32_e32 v180, v97, v97
	v_max_f32_e32 v182, v96, v96
	v_max_f32_e32 v180, v182, v180
	v_max3_f32 v180, v180, v98, v99
	v_max3_f32 v180, v180, v100, v101
	v_max3_f32 v180, v180, v102, v103
	v_max3_f32 v180, v180, v104, v105
	v_max3_f32 v180, v180, v106, v107
	v_max3_f32 v180, v180, v108, v109
	v_max3_f32 v180, v180, v110, v111
	v_max3_f32 v180, v180, v64, v65
	v_max3_f32 v180, v180, v66, v67
	v_max3_f32 v180, v180, v68, v69
	v_max3_f32 v180, v180, v70, v71
	v_max3_f32 v180, v180, v72, v73
	v_max3_f32 v180, v180, v74, v75
	v_max3_f32 v180, v180, v76, v77
	v_max3_f32 v180, v180, v78, v79
	v_mov_b32_e32 v182, v180
	s_nop 1
	v_permlane32_swap_b32_e32 v180, v182
	v_max_f32_e32 v182, v182, v182
	v_max_f32_e32 v180, v180, v180
	v_max_f32_e32 v180, v180, v182
	s_waitcnt lgkmcnt(4)
	v_mfma_f32_32x32x16_bf16 v[0:15], v[80:83], v[214:217], v[0:15]
	ds_read_b64_tr_b16 v[214:215], v191 offset:0x200
	ds_read_b64_tr_b16 v[216:217], v191 offset:0xa00
	v_mfma_f32_32x32x16_bf16 v[0:15], v[84:87], v[218:221], v[0:15]
	ds_read_b64_tr_b16 v[218:219], v191 offset:0x1200
	ds_read_b64_tr_b16 v[220:221], v191 offset:0x1a00
	s_waitcnt lgkmcnt(4)
	v_mfma_f32_32x32x16_bf16 v[0:15], v[88:91], v[222:225], v[0:15]
	ds_read_b64_tr_b16 v[222:223], v191 offset:0x2200
	ds_read_b64_tr_b16 v[224:225], v191 offset:0x2a00
	v_mfma_f32_32x32x16_bf16 v[0:15], v[92:95], v[234:237], v[0:15]
	ds_read_b64_tr_b16 v[234:235], v191 offset:0x3200
	ds_read_b64_tr_b16 v[236:237], v191 offset:0x3a00
	s_waitcnt lgkmcnt(4)
	v_mfma_f32_32x32x16_bf16 v[48:63], v[80:83], v[214:217], v[48:63]
	ds_read_b64_tr_b16 v[214:215], v191 offset:0x400
	ds_read_b64_tr_b16 v[216:217], v191 offset:0xc00
	v_mfma_f32_32x32x16_bf16 v[48:63], v[84:87], v[218:221], v[48:63]
	ds_read_b64_tr_b16 v[218:219], v191 offset:0x1400
	ds_read_b64_tr_b16 v[220:221], v191 offset:0x1c00
	s_waitcnt lgkmcnt(4)
	v_mfma_f32_32x32x16_bf16 v[48:63], v[88:91], v[222:225], v[48:63]
	ds_read_b64_tr_b16 v[222:223], v191 offset:0x2400
	ds_read_b64_tr_b16 v[224:225], v191 offset:0x2c00
	v_mfma_f32_32x32x16_bf16 v[48:63], v[92:95], v[234:237], v[48:63]
	ds_read_b64_tr_b16 v[234:235], v191 offset:0x3400
	ds_read_b64_tr_b16 v[236:237], v191 offset:0x3c00
	s_waitcnt lgkmcnt(4)
	v_mfma_f32_32x32x16_bf16 v[32:47], v[80:83], v[214:217], v[32:47]
	ds_read_b64_tr_b16 v[214:215], v191 offset:0x600
	ds_read_b64_tr_b16 v[216:217], v191 offset:0xe00
	v_mfma_f32_32x32x16_bf16 v[32:47], v[84:87], v[218:221], v[32:47]
	ds_read_b64_tr_b16 v[218:219], v191 offset:0x1600
	ds_read_b64_tr_b16 v[220:221], v191 offset:0x1e00
	s_waitcnt lgkmcnt(4)
	v_mfma_f32_32x32x16_bf16 v[32:47], v[88:91], v[222:225], v[32:47]
	ds_read_b64_tr_b16 v[222:223], v191 offset:0x2600
	ds_read_b64_tr_b16 v[224:225], v191 offset:0x2e00
	v_mfma_f32_32x32x16_bf16 v[32:47], v[92:95], v[234:237], v[32:47]
	ds_read_b64_tr_b16 v[234:235], v191 offset:0x3600
	ds_read_b64_tr_b16 v[236:237], v191 offset:0x3e00
	s_waitcnt lgkmcnt(4)
	v_mfma_f32_32x32x16_bf16 v[16:31], v[80:83], v[214:217], v[16:31]
	v_mfma_f32_32x32x16_bf16 v[16:31], v[84:87], v[218:221], v[16:31]
	s_waitcnt lgkmcnt(0)
	v_mfma_f32_32x32x16_bf16 v[16:31], v[88:91], v[222:225], v[16:31]
	s_waitcnt vmcnt(4)
	ds_write_b128 v195, v[170:173] offset:49152
	ds_write_b128 v196, v[174:177] offset:49152
	v_mfma_f32_32x32x16_bf16 v[16:31], v[92:95], v[234:237], v[16:31]
	v_cmp_ge_f32_e32 vcc, s45, v180
	s_cmp_eq_u64 vcc, exec
	v_mov_b32_e32 v170, 1.0
	s_cbranch_scc0 .LBB0_166

; #define SBAR() __builtin_amdgcn_sched_barrier(0)
; #define KWRITE(b, src0, src1) do { if constexpr (ND0 == 4) { *(bf16x8*)(K_lds + (b) * SHM_K + KSWZ(kr, kcb)) = src0; } \
;     else { int kc = sc * 2; *(bf16x8*)(K_lds + (b) * SHM_K + KSWZ(sr, kc)) = src0; *(bf16x8*)(K_lds + (b) * SHM_K + KSWZ(32 + sr, kc)) = src1; } } while (0)
; template <int OFF> __device__ __forceinline__ s16x4 tr_read(int vb) {
;   s16x4 r; asm volatile("ds_read_b64_tr_b16 %0, %1 offset:%2" : "=&v"(r) : "v"(vb), "i"(OFF) : "memory"); return r;
; }
; template <int D0> __device__ __forceinline__ void pv_one(f32x16& od, int vb, bf16x8 pa0, bf16x8 pa1, bf16x8 pa2, bf16x8 pa3) {
;   const s16x4 l0 = tr_read<v_rd_off(D0, 0, 0)>(vb), h0 = tr_read<v_rd_off(D0, 0, 1)>(vb), l1 = tr_read<v_rd_off(D0, 1, 0)>(vb), h1 = tr_read<v_rd_off(D0, 1, 1)>(vb);
;   const s16x4 l2 = tr_read<v_rd_off(D0, 2, 0)>(vb), h2 = tr_read<v_rd_off(D0, 2, 1)>(vb), l3 = tr_read<v_rd_off(D0, 3, 0)>(vb), h3 = tr_read<v_rd_off(D0, 3, 1)>(vb);
;   asm volatile("s_waitcnt lgkmcnt(0)" ::: "memory"); SBAR();
;     ...
;   od = __builtin_amdgcn_mfma_f32_32x32x16_bf16(pa0, PK(l0, h0), od, 0, 0, 0);
;   od = __builtin_amdgcn_mfma_f32_32x32x16_bf16(pa1, PK(l1, h1), od, 0, 0, 0);
;   od = __builtin_amdgcn_mfma_f32_32x32x16_bf16(pa2, PK(l2, h2), od, 0, 0, 0);
;   od = __builtin_amdgcn_mfma_f32_32x32x16_bf16(pa3, PK(l3, h3), od, 0, 0, 0);
;     ...
; }
; __device__ __forceinline__ void pv_d0(f32x16* o, int vb, bf16x8 pa0, bf16x8 pa1, bf16x8 pa2, bf16x8 pa3) {
;   pv_one<0>(o[0], vb, pa0, pa1, pa2, pa3); pv_one<1>(o[1], vb, pa0, pa1, pa2, pa3); pv_one<2>(o[2], vb, pa0, pa1, pa2, pa3); pv_one<3>(o[3], vb, pa0, pa1, pa2, pa3);
; }
; template <int ND0, int LDQ, int LDK, int LDO> ...
;     ...
;   for (int j = 1; j + 1 < NT; j += 2) {
;     SBAR(); qkt<ND0>(pB0, pB1, Kq1, qr, r32, hi);
;     finishSM(pA0, pA1, alA, l_reg, pa0, pa1, pa2, pa3); SBAR();
;     SLOAD_B((j + 2) * KVBLK); SBAR();
;     pv_d0(o, vb0, pa0, pa1, pa2, pa3); KWRITE(0, ks0a, ks1a); PSM(pB0, pB1, mnB, alB);
;     __syncthreads(); SWAIT(); VWRITE_A(0);
;     RESC(alB); __syncthreads();
;     SBAR(); qkt<ND0>(pA0, pA1, Kq0, qr, r32, hi);
;     finishSM(pB0, pB1, alB, l_reg, pa0, pa1, pa2, pa3); SBAR();
;     if (j + 3 < NT) SLOAD_A((j + 3) * KVBLK); SBAR();
;     pv_d0(o, vb0 + (int)SHM_V, pa0, pa1, pa2, pa3); KWRITE(1, ks0b, ks1b); PSM(pA0, pA1, mnA, alA);
.LBB0_215:
	v_max_f32_e32 v252, v97, v97
	v_max_f32_e32 v253, v96, v96
	v_max_f32_e32 v252, v253, v252
	v_max3_f32 v252, v252, v98, v99
	v_max3_f32 v252, v252, v100, v101
	v_max3_f32 v252, v252, v102, v103
	v_max3_f32 v252, v252, v104, v105
	v_max3_f32 v252, v252, v106, v107
	v_max3_f32 v252, v252, v108, v109
	v_max3_f32 v252, v252, v110, v111
	v_max3_f32 v252, v252, v80, v81
	v_max3_f32 v252, v252, v82, v83
	v_max3_f32 v252, v252, v84, v85
	v_max3_f32 v252, v252, v86, v87
	v_max3_f32 v252, v252, v88, v89
	v_max3_f32 v252, v252, v90, v91
	v_max3_f32 v252, v252, v92, v93
	v_max3_f32 v252, v252, v94, v95
	v_mov_b32_e32 v253, v252
	s_nop 1
	v_permlane32_swap_b32_e32 v252, v253
	v_max_f32_e32 v253, v253, v253
	v_max_f32_e32 v252, v252, v252
	v_max_f32_e32 v252, v252, v253
	s_waitcnt lgkmcnt(4)
	v_mfma_f32_32x32x16_bf16 v[0:15], v[64:67], v[204:207], v[0:15]
	ds_read_b64_tr_b16 v[204:205], v192 offset:0x200
	ds_read_b64_tr_b16 v[206:207], v192 offset:0xa00
	v_mfma_f32_32x32x16_bf16 v[0:15], v[68:71], v[208:211], v[0:15]
	ds_read_b64_tr_b16 v[208:209], v192 offset:0x1200
	ds_read_b64_tr_b16 v[210:211], v192 offset:0x1a00
	s_waitcnt lgkmcnt(4)
	v_mfma_f32_32x32x16_bf16 v[0:15], v[72:75], v[212:215], v[0:15]
	ds_read_b64_tr_b16 v[212:213], v192 offset:0x2200
	ds_read_b64_tr_b16 v[214:215], v192 offset:0x2a00
	v_mfma_f32_32x32x16_bf16 v[0:15], v[76:79], v[216:219], v[0:15]
	ds_read_b64_tr_b16 v[216:217], v192 offset:0x3200
	ds_read_b64_tr_b16 v[218:219], v192 offset:0x3a00
	s_waitcnt lgkmcnt(4)
	v_mfma_f32_32x32x16_bf16 v[48:63], v[64:67], v[204:207], v[48:63]
	ds_read_b64_tr_b16 v[204:205], v192 offset:0x400
	ds_read_b64_tr_b16 v[206:207], v192 offset:0xc00
	v_mfma_f32_32x32x16_bf16 v[48:63], v[68:71], v[208:211], v[48:63]
	ds_read_b64_tr_b16 v[208:209], v192 offset:0x1400
	ds_read_b64_tr_b16 v[210:211], v192 offset:0x1c00
	s_waitcnt lgkmcnt(4)
	v_mfma_f32_32x32x16_bf16 v[48:63], v[72:75], v[212:215], v[48:63]
	ds_read_b64_tr_b16 v[212:213], v192 offset:0x2400
	ds_read_b64_tr_b16 v[214:215], v192 offset:0x2c00
	v_mfma_f32_32x32x16_bf16 v[48:63], v[76:79], v[216:219], v[48:63]
	ds_read_b64_tr_b16 v[216:217], v192 offset:0x3400
	ds_read_b64_tr_b16 v[218:219], v192 offset:0x3c00
	s_waitcnt lgkmcnt(4)
	v_mfma_f32_32x32x16_bf16 v[32:47], v[64:67], v[204:207], v[32:47]
	ds_read_b64_tr_b16 v[204:205], v192 offset:0x600
	ds_read_b64_tr_b16 v[206:207], v192 offset:0xe00
	v_mfma_f32_32x32x16_bf16 v[32:47], v[68:71], v[208:211], v[32:47]
	ds_read_b64_tr_b16 v[208:209], v192 offset:0x1600
	ds_read_b64_tr_b16 v[210:211], v192 offset:0x1e00
	s_waitcnt lgkmcnt(4)
	v_mfma_f32_32x32x16_bf16 v[32:47], v[72:75], v[212:215], v[32:47]
	ds_read_b64_tr_b16 v[212:213], v192 offset:0x2600
	ds_read_b64_tr_b16 v[214:215], v192 offset:0x2e00
	v_mfma_f32_32x32x16_bf16 v[32:47], v[76:79], v[216:219], v[32:47]
	ds_read_b64_tr_b16 v[216:217], v192 offset:0x3600
	ds_read_b64_tr_b16 v[218:219], v192 offset:0x3e00
	s_waitcnt lgkmcnt(4)
	v_mfma_f32_32x32x16_bf16 v[16:31], v[64:67], v[204:207], v[16:31]
	v_mfma_f32_32x32x16_bf16 v[16:31], v[68:71], v[208:211], v[16:31]
	s_waitcnt lgkmcnt(0)
	v_mfma_f32_32x32x16_bf16 v[16:31], v[72:75], v[212:215], v[16:31]
	s_waitcnt vmcnt(3)
	ds_write_b128 v195, v[138:141] offset:32768
	v_mfma_f32_32x32x16_bf16 v[16:31], v[76:79], v[216:219], v[16:31]
	v_cmp_ge_f32_e32 vcc, s45, v252
	s_cmp_eq_u64 vcc, exec
	v_mov_b32_e32 v203, 1.0
	s_cbranch_scc0 .LBB0_231

; #define SBAR() __builtin_amdgcn_sched_barrier(0)
; #define KWRITE(b, src0, src1) do { if constexpr (ND0 == 4) { *(bf16x8*)(K_lds + (b) * SHM_K + KSWZ(kr, kcb)) = src0; } \
;     else { int kc = sc * 2; *(bf16x8*)(K_lds + (b) * SHM_K + KSWZ(sr, kc)) = src0; *(bf16x8*)(K_lds + (b) * SHM_K + KSWZ(32 + sr, kc)) = src1; } } while (0)
; template <int OFF> __device__ __forceinline__ s16x4 tr_read(int vb) {
;   s16x4 r; asm volatile("ds_read_b64_tr_b16 %0, %1 offset:%2" : "=&v"(r) : "v"(vb), "i"(OFF) : "memory"); return r;
; }
; template <int D0> __device__ __forceinline__ void pv_one(f32x16& od, int vb, bf16x8 pa0, bf16x8 pa1, bf16x8 pa2, bf16x8 pa3) {
;   const s16x4 l0 = tr_read<v_rd_off(D0, 0, 0)>(vb), h0 = tr_read<v_rd_off(D0, 0, 1)>(vb), l1 = tr_read<v_rd_off(D0, 1, 0)>(vb), h1 = tr_read<v_rd_off(D0, 1, 1)>(vb);
;   const s16x4 l2 = tr_read<v_rd_off(D0, 2, 0)>(vb), h2 = tr_read<v_rd_off(D0, 2, 1)>(vb), l3 = tr_read<v_rd_off(D0, 3, 0)>(vb), h3 = tr_read<v_rd_off(D0, 3, 1)>(vb);
;   asm volatile("s_waitcnt lgkmcnt(0)" ::: "memory"); SBAR();
;     ...
;   od = __builtin_amdgcn_mfma_f32_32x32x16_bf16(pa0, PK(l0, h0), od, 0, 0, 0);
;   od = __builtin_amdgcn_mfma_f32_32x32x16_bf16(pa1, PK(l1, h1), od, 0, 0, 0);
;   od = __builtin_amdgcn_mfma_f32_32x32x16_bf16(pa2, PK(l2, h2), od, 0, 0, 0);
;   od = __builtin_amdgcn_mfma_f32_32x32x16_bf16(pa3, PK(l3, h3), od, 0, 0, 0);
;     ...
; }
; __device__ __forceinline__ void pv_d0(f32x16* o, int vb, bf16x8 pa0, bf16x8 pa1, bf16x8 pa2, bf16x8 pa3) {
;   pv_one<0>(o[0], vb, pa0, pa1, pa2, pa3); pv_one<1>(o[1], vb, pa0, pa1, pa2, pa3); pv_one<2>(o[2], vb, pa0, pa1, pa2, pa3); pv_one<3>(o[3], vb, pa0, pa1, pa2, pa3);
; }
; template <int ND0, int LDQ, int LDK, int LDO> ...
;     ...
;   for (int j = 1; j + 1 < NT; j += 2) {
;     SBAR(); qkt<ND0>(pB0, pB1, Kq1, qr, r32, hi);
;     finishSM(pA0, pA1, alA, l_reg, pa0, pa1, pa2, pa3); SBAR();
;     SLOAD_B((j + 2) * KVBLK); SBAR();
;     pv_d0(o, vb0, pa0, pa1, pa2, pa3); KWRITE(0, ks0a, ks1a); PSM(pB0, pB1, mnB, alB);
;     __syncthreads(); SWAIT(); VWRITE_A(0);
;     RESC(alB); __syncthreads();
;     SBAR(); qkt<ND0>(pA0, pA1, Kq0, qr, r32, hi);
;     finishSM(pB0, pB1, alB, l_reg, pa0, pa1, pa2, pa3); SBAR();
;     if (j + 3 < NT) SLOAD_A((j + 3) * KVBLK); SBAR();
;     pv_d0(o, vb0 + (int)SHM_V, pa0, pa1, pa2, pa3); KWRITE(1, ks0b, ks1b); PSM(pA0, pA1, mnA, alA);
.LBB0_223:
	v_max_f32_e32 v252, v97, v97
	v_max_f32_e32 v253, v96, v96
	v_max_f32_e32 v252, v253, v252
	v_max3_f32 v252, v252, v98, v99
	v_max3_f32 v252, v252, v100, v101
	v_max3_f32 v252, v252, v102, v103
	v_max3_f32 v252, v252, v104, v105
	v_max3_f32 v252, v252, v106, v107
	v_max3_f32 v252, v252, v108, v109
	v_max3_f32 v252, v252, v110, v111
	v_max3_f32 v252, v252, v64, v65
	v_max3_f32 v252, v252, v66, v67
	v_max3_f32 v252, v252, v68, v69
	v_max3_f32 v252, v252, v70, v71
	v_max3_f32 v252, v252, v72, v73
	v_max3_f32 v252, v252, v74, v75
	v_max3_f32 v252, v252, v76, v77
	v_max3_f32 v252, v252, v78, v79
	v_mov_b32_e32 v253, v252
	s_nop 1
	v_permlane32_swap_b32_e32 v252, v253
	v_max_f32_e32 v253, v253, v253
	v_max_f32_e32 v252, v252, v252
	v_max_f32_e32 v252, v252, v253
	s_waitcnt lgkmcnt(4)
	v_mfma_f32_32x32x16_bf16 v[0:15], v[80:83], v[174:177], v[0:15]
	ds_read_b64_tr_b16 v[174:175], v190 offset:0x200
	ds_read_b64_tr_b16 v[176:177], v190 offset:0xa00
	v_mfma_f32_32x32x16_bf16 v[0:15], v[84:87], v[206:209], v[0:15]
	ds_read_b64_tr_b16 v[206:207], v190 offset:0x1200
	ds_read_b64_tr_b16 v[208:209], v190 offset:0x1a00
	s_waitcnt lgkmcnt(4)
	v_mfma_f32_32x32x16_bf16 v[0:15], v[88:91], v[210:213], v[0:15]
	ds_read_b64_tr_b16 v[210:211], v190 offset:0x2200
	ds_read_b64_tr_b16 v[212:213], v190 offset:0x2a00
	v_mfma_f32_32x32x16_bf16 v[0:15], v[92:95], v[214:217], v[0:15]
	ds_read_b64_tr_b16 v[214:215], v190 offset:0x3200
	ds_read_b64_tr_b16 v[216:217], v190 offset:0x3a00
	s_waitcnt lgkmcnt(4)
	v_mfma_f32_32x32x16_bf16 v[48:63], v[80:83], v[174:177], v[48:63]
	ds_read_b64_tr_b16 v[174:175], v190 offset:0x400
	ds_read_b64_tr_b16 v[176:177], v190 offset:0xc00
	v_mfma_f32_32x32x16_bf16 v[48:63], v[84:87], v[206:209], v[48:63]
	ds_read_b64_tr_b16 v[206:207], v190 offset:0x1400
	ds_read_b64_tr_b16 v[208:209], v190 offset:0x1c00
	s_waitcnt lgkmcnt(4)
	v_mfma_f32_32x32x16_bf16 v[48:63], v[88:91], v[210:213], v[48:63]
	ds_read_b64_tr_b16 v[210:211], v190 offset:0x2400
	ds_read_b64_tr_b16 v[212:213], v190 offset:0x2c00
	v_mfma_f32_32x32x16_bf16 v[48:63], v[92:95], v[214:217], v[48:63]
	ds_read_b64_tr_b16 v[214:215], v190 offset:0x3400
	ds_read_b64_tr_b16 v[216:217], v190 offset:0x3c00
	s_waitcnt lgkmcnt(4)
	v_mfma_f32_32x32x16_bf16 v[32:47], v[80:83], v[174:177], v[32:47]
	ds_read_b64_tr_b16 v[174:175], v190 offset:0x600
	ds_read_b64_tr_b16 v[176:177], v190 offset:0xe00
	v_mfma_f32_32x32x16_bf16 v[32:47], v[84:87], v[206:209], v[32:47]
	ds_read_b64_tr_b16 v[206:207], v190 offset:0x1600
	ds_read_b64_tr_b16 v[208:209], v190 offset:0x1e00
	s_waitcnt lgkmcnt(4)
	v_mfma_f32_32x32x16_bf16 v[32:47], v[88:91], v[210:213], v[32:47]
	ds_read_b64_tr_b16 v[210:211], v190 offset:0x2600
	ds_read_b64_tr_b16 v[212:213], v190 offset:0x2e00
	v_mfma_f32_32x32x16_bf16 v[32:47], v[92:95], v[214:217], v[32:47]
	ds_read_b64_tr_b16 v[214:215], v190 offset:0x3600
	ds_read_b64_tr_b16 v[216:217], v190 offset:0x3e00
	s_waitcnt lgkmcnt(4)
	v_mfma_f32_32x32x16_bf16 v[16:31], v[80:83], v[174:177], v[16:31]
	v_mfma_f32_32x32x16_bf16 v[16:31], v[84:87], v[206:209], v[16:31]
	s_waitcnt lgkmcnt(0)
	v_mfma_f32_32x32x16_bf16 v[16:31], v[88:91], v[210:213], v[16:31]
	s_waitcnt vmcnt(3)
	ds_write_b128 v195, v[150:153] offset:49152
	v_mfma_f32_32x32x16_bf16 v[16:31], v[92:95], v[214:217], v[16:31]
	v_cmp_ge_f32_e32 vcc, s45, v252
	s_cmp_eq_u64 vcc, exec
	v_mov_b32_e32 v150, 1.0
	s_cbranch_scc0 .LBB0_233
